# v19: v17 + nt on the final RMSNorm phase x loads
# speedup vs baseline: 1.0042x; 1.0042x over previous
; __device__ __forceinline__ float bperm(float v, int srclane) { return __int_as_float(__builtin_amdgcn_ds_bpermute(srclane << 2, __float_as_int(v))); }
; __device__ __forceinline__ float bperm(float v, int srclane) { return __int_as_float(__builtin_amdgcn_ds_bpermute(srclane << 2, __float_as_int(v))); }
; __device__ __forceinline__ void phase_final(float* x, const float* g, int gw, int NGW, int lane) {
;     ...
;     for (int r0 = gw; r0 < M; r0 += 4 * NGW) { f32x4 v[4][4]; float s[4];
; #pragma unroll
;         for (int q = 0; q < 4; ++q) { const int r = (r0 + q * NGW < M) ? r0 + q * NGW : r0; const f32x4* xr = (const f32x4*)(x + (size_t)r * D) + lane; s[q] = 0.f;
; #pragma unroll
;             for (int j = 0; j < 4; ++j) { v[q][j] = xr[64 * j]; s[q] += (v[q][j].x * v[q][j].x + v[q][j].y * v[q][j].y) + (v[q][j].z * v[q][j].z + v[q][j].w * v[q][j].w); } }
; #pragma unroll
;         for (int o = 1; o < 64; o <<= 1) {
; #pragma unroll
;             for (int q = 0; q < 4; ++q) s[q] += bperm(s[q], lane ^ o); }
.LBB0_1602:
	s_ashr_i32 s11, s10, 31
	s_lshl_b64 s[0:1], s[10:11], 12
	v_lshl_add_u64 v[82:83], v[80:81], 0, s[0:1]
	s_waitcnt lgkmcnt(2)
	global_load_dwordx4 v[20:23], v[82:83], off nt
	global_load_dwordx4 v[24:27], v[82:83], off offset:1024 nt
	s_waitcnt lgkmcnt(0)
	global_load_dwordx4 v[16:19], v[82:83], off offset:3072 nt
	global_load_dwordx4 v[28:31], v[82:83], off offset:2048 nt
	s_add_i32 s0, s10, s8
	s_cmpk_lt_i32 s0, 0x4000
	s_cselect_b32 s2, s0, s10
	s_ashr_i32 s3, s2, 31
	s_lshl_b64 s[2:3], s[2:3], 12
	s_add_i32 s6, s9, s10
	s_cmpk_lt_i32 s6, 0x4000
	v_lshl_add_u64 v[32:33], v[80:81], 0, s[2:3]
	s_cselect_b64 s[12:13], -1, 0
	global_load_dwordx4 v[60:63], v[32:33], off nt
	global_load_dwordx4 v[52:55], v[32:33], off offset:1024 nt
	global_load_dwordx4 v[76:79], v[32:33], off offset:2048 nt
	global_load_dwordx4 v[72:75], v[32:33], off offset:3072 nt
	s_and_b64 s[2:3], s[12:13], exec
	s_cselect_b32 s2, s6, s10
	s_ashr_i32 s3, s2, 31
	s_lshl_b64 s[2:3], s[2:3], 12
	v_lshl_add_u64 v[32:33], v[80:81], 0, s[2:3]
	global_load_dwordx4 v[68:71], v[32:33], off nt
	global_load_dwordx4 v[64:67], v[32:33], off offset:1024 nt
	global_load_dwordx4 v[56:59], v[32:33], off offset:2048 nt
	global_load_dwordx4 v[48:51], v[32:33], off offset:3072 nt
	s_add_i32 s2, s14, s10
	s_cmpk_lt_i32 s2, 0x4000
	s_cselect_b64 s[4:5], -1, 0
	s_and_b64 s[16:17], s[4:5], exec
	s_cselect_b32 s10, s2, s10
	s_ashr_i32 s11, s10, 31
	s_lshl_b64 s[10:11], s[10:11], 12
	v_lshl_add_u64 v[92:93], v[80:81], 0, s[10:11]
	global_load_dwordx4 v[44:47], v[92:93], off nt
	global_load_dwordx4 v[40:43], v[92:93], off offset:1024 nt
	global_load_dwordx4 v[36:39], v[92:93], off offset:2048 nt
	global_load_dwordx4 v[32:35], v[92:93], off offset:3072 nt
	s_cmpk_gt_i32 s0, 0x3fff
	s_waitcnt vmcnt(15)
	v_pk_mul_f32 v[92:93], v[22:23], v[22:23]
	v_pk_mul_f32 v[94:95], v[20:21], v[20:21]
	s_waitcnt vmcnt(14)
	v_pk_mul_f32 v[96:97], v[26:27], v[26:27]
	v_pk_mul_f32 v[98:99], v[24:25], v[24:25]
	v_pk_mov_b32 v[104:105], v[94:95], v[92:93] op_sel:[1,0]
	v_mov_b32_e32 v95, v93
	v_pk_mov_b32 v[92:93], v[98:99], v[96:97] op_sel:[1,0]
	v_mov_b32_e32 v99, v97
	s_waitcnt vmcnt(13)
	v_mul_f32_e32 v103, v17, v17
	s_waitcnt vmcnt(12)
	v_mul_f32_e32 v100, v29, v29
	v_mul_f32_e32 v102, v31, v31
	v_pk_add_f32 v[94:95], v[104:105], v[94:95]
	v_pk_add_f32 v[92:93], v[92:93], v[98:99]
	v_mul_f32_e32 v91, v16, v16
	v_mul_f32_e32 v106, v18, v18
	v_mul_f32_e32 v107, v19, v19
	v_pk_fma_f32 v[96:97], v[28:29], v[28:29], v[100:101] op_sel_hi:[1,1,0]
	v_pk_fma_f32 v[100:101], v[30:31], v[30:31], v[102:103] op_sel_hi:[1,1,0]
	v_pk_add_f32 v[94:95], v[94:95], v[94:95] op_sel:[0,1] op_sel_hi:[1,0]
	v_pk_add_f32 v[92:93], v[92:93], v[92:93] op_sel:[0,1] op_sel_hi:[1,0]
	v_mov_b32_e32 v97, v106
	v_mov_b32_e32 v101, v107
	v_mov_b32_e32 v95, v91
	v_mov_b32_e32 v93, v103
	v_pk_add_f32 v[96:97], v[96:97], v[100:101]
	v_pk_add_f32 v[92:93], v[94:95], v[92:93]
	s_waitcnt vmcnt(11)
	v_mul_f32_e32 v91, v61, v61
	v_pk_add_f32 v[92:93], v[92:93], v[96:97]
	v_mul_f32_e32 v98, v63, v63
	v_add_f32_e32 v92, v92, v93
	ds_bpermute_b32 v93, v84, v92
	s_waitcnt vmcnt(10)
	v_mul_f32_e32 v99, v53, v53
	v_mul_f32_e32 v100, v55, v55
	s_waitcnt vmcnt(9)
	v_mul_f32_e32 v101, v77, v77
	v_mul_f32_e32 v102, v79, v79
	s_waitcnt lgkmcnt(0)
	v_add_f32_e32 v92, v92, v93
	ds_bpermute_b32 v93, v85, v92
	v_fmac_f32_e32 v91, v60, v60
	v_fmac_f32_e32 v98, v62, v62
	v_fmac_f32_e32 v99, v52, v52
	v_fmac_f32_e32 v100, v54, v54
	s_waitcnt lgkmcnt(0)
	v_add_f32_e32 v92, v92, v93
	ds_bpermute_b32 v93, v86, v92
	s_waitcnt vmcnt(8)
	v_mul_f32_e32 v103, v73, v73
	v_mul_f32_e32 v104, v75, v75
	v_fmac_f32_e32 v101, v76, v76
	v_fmac_f32_e32 v102, v78, v78
	s_waitcnt lgkmcnt(0)
	v_add_f32_e32 v92, v92, v93
	ds_bpermute_b32 v93, v87, v92
	v_add_f32_e32 v91, v91, v98
	v_add_f32_e32 v94, v99, v100
	v_fmac_f32_e32 v103, v72, v72
	v_fmac_f32_e32 v104, v74, v74
	s_waitcnt lgkmcnt(0)
	v_add_f32_e32 v92, v92, v93
	ds_bpermute_b32 v93, v88, v92
	v_add_f32_e32 v95, v101, v102
	v_add_f32_e32 v91, v91, v94
	v_add_f32_e32 v96, v103, v104
	v_add_f32_e32 v91, v91, v95
	s_waitcnt lgkmcnt(0)
	v_add_f32_e32 v92, v92, v93
	ds_bpermute_b32 v93, v89, v92
	v_add_f32_e32 v91, v91, v96
	s_waitcnt vmcnt(7)
; __device__ __forceinline__ float bperm(float v, int srclane) { return __int_as_float(__builtin_amdgcn_ds_bpermute(srclane << 2, __float_as_int(v))); }
; __device__ __forceinline__ float bperm(float v, int srclane) { return __int_as_float(__builtin_amdgcn_ds_bpermute(srclane << 2, __float_as_int(v))); }
; __device__ __forceinline__ void phase_final(float* x, const float* g, int gw, int NGW, int lane) {
;     ...
;             for (int j = 0; j < 4; ++j) { v[q][j] = xr[64 * j]; s[q] += (v[q][j].x * v[q][j].x + v[q][j].y * v[q][j].y) + (v[q][j].z * v[q][j].z + v[q][j].w * v[q][j].w); } }
; #pragma unroll
;         for (int o = 1; o < 64; o <<= 1) {
; #pragma unroll
;             for (int q = 0; q < 4; ++q) s[q] += bperm(s[q], lane ^ o); }
; #pragma unroll
;         for (int q = 0; q < 4; ++q) { const int r = r0 + q * NGW; if (r < M) { const float rs = rsqrtf(s[q] * (1.f / D) + 1e-6f); f32x4* xr = (f32x4*)(x + (size_t)r * D) + lane;
; #pragma unroll
;                 for (int j = 0; j < 4; ++j) xr[64 * j] = (f32x4){v[q][j].x * rs * gv[j].x, v[q][j].y * rs * gv[j].y, v[q][j].z * rs * gv[j].z, v[q][j].w * rs * gv[j].w}; } }
	v_mul_f32_e32 v94, v69, v69
	v_mul_f32_e32 v95, v71, v71
	s_waitcnt vmcnt(6)
	v_mul_f32_e32 v96, v65, v65
	s_waitcnt lgkmcnt(0)
	v_add_f32_e32 v92, v92, v93
	v_fmamk_f32 v92, v92, 0x3a800000, v90
	v_mul_f32_e32 v93, 0x4b800000, v92
	v_cmp_gt_f32_e32 vcc, s15, v92
	v_mul_f32_e32 v97, v67, v67
	s_waitcnt vmcnt(5)
	v_mul_f32_e32 v98, v57, v57
	v_cndmask_b32_e32 v92, v92, v93, vcc
	v_rsq_f32_e32 v92, v92
	v_mul_f32_e32 v99, v59, v59
	v_fmac_f32_e32 v94, v68, v68
	v_fmac_f32_e32 v95, v70, v70
	v_fmac_f32_e32 v96, v64, v64
	v_fmac_f32_e32 v97, v66, v66
	v_fmac_f32_e32 v98, v56, v56
	v_fmac_f32_e32 v99, v58, v58
	v_add_f32_e32 v94, v94, v95
	v_add_f32_e32 v95, v96, v97
	v_add_f32_e32 v93, v98, v99
	v_add_f32_e32 v94, v94, v95
	v_add_f32_e32 v93, v94, v93
	v_mul_f32_e32 v94, 0x45800000, v92
	v_cndmask_b32_e32 v92, v92, v94, vcc
	s_waitcnt vmcnt(4)
	v_mul_f32_e32 v100, v49, v49
	v_pk_mul_f32 v[94:95], v[16:17], v[92:93] op_sel_hi:[1,0]
	v_mul_f32_e32 v16, v51, v51
	v_fmac_f32_e32 v100, v48, v48
	v_fmac_f32_e32 v16, v50, v50
	v_add_f32_e32 v16, v100, v16
	v_pk_mul_f32 v[20:21], v[20:21], v[92:93] op_sel_hi:[1,0]
	v_pk_mul_f32 v[22:23], v[22:23], v[92:93] op_sel_hi:[1,0]
	v_pk_mul_f32 v[24:25], v[24:25], v[92:93] op_sel_hi:[1,0]
	v_pk_mul_f32 v[26:27], v[26:27], v[92:93] op_sel_hi:[1,0]
	v_pk_mul_f32 v[28:29], v[28:29], v[92:93] op_sel_hi:[1,0]
	v_pk_mul_f32 v[30:31], v[30:31], v[92:93] op_sel_hi:[1,0]
	v_add_f32_e32 v16, v93, v16
	s_waitcnt vmcnt(3)
	v_mul_f32_e32 v17, v45, v45
	v_mul_f32_e32 v93, v47, v47
	v_fmac_f32_e32 v17, v44, v44
	v_fmac_f32_e32 v93, v46, v46
	v_add_f32_e32 v17, v17, v93
	s_waitcnt vmcnt(2)
	v_mul_f32_e32 v93, v41, v41
	v_mul_f32_e32 v96, v43, v43
	v_fmac_f32_e32 v93, v40, v40
	v_fmac_f32_e32 v96, v42, v42
	v_add_f32_e32 v93, v93, v96
	v_add_f32_e32 v17, v17, v93
	s_waitcnt vmcnt(1)
	v_mul_f32_e32 v93, v37, v37
	v_mul_f32_e32 v96, v39, v39
	v_fmac_f32_e32 v93, v36, v36
	v_fmac_f32_e32 v96, v38, v38
	v_add_f32_e32 v93, v93, v96
	v_add_f32_e32 v17, v17, v93
	s_waitcnt vmcnt(0)
	v_mul_f32_e32 v93, v33, v33
	v_mul_f32_e32 v96, v35, v35
	v_fmac_f32_e32 v93, v32, v32
	v_fmac_f32_e32 v96, v34, v34
	v_add_f32_e32 v93, v93, v96
	v_add_f32_e32 v17, v17, v93
	ds_bpermute_b32 v96, v84, v91
	ds_bpermute_b32 v97, v84, v16
	ds_bpermute_b32 v98, v84, v17
	v_pk_mul_f32 v[92:93], v[18:19], v[92:93] op_sel_hi:[1,0]
	v_pk_mul_f32 v[18:19], v[14:15], v[22:23]
	s_waitcnt lgkmcnt(2)
	v_add_f32_e32 v22, v91, v96
	s_waitcnt lgkmcnt(1)
	v_add_f32_e32 v23, v16, v97
	s_waitcnt lgkmcnt(0)
	v_add_f32_e32 v91, v17, v98
	ds_bpermute_b32 v96, v85, v22
	ds_bpermute_b32 v97, v85, v23
	ds_bpermute_b32 v98, v85, v91
	v_pk_mul_f32 v[16:17], v[12:13], v[20:21]
	global_store_dwordx4 v[82:83], v[16:19], off
	s_waitcnt lgkmcnt(2)
	v_add_f32_e32 v20, v22, v96
	s_waitcnt lgkmcnt(1)
	v_add_f32_e32 v21, v23, v97
	s_waitcnt lgkmcnt(0)
	v_add_f32_e32 v22, v91, v98
	ds_bpermute_b32 v23, v86, v20
	ds_bpermute_b32 v91, v86, v21
	ds_bpermute_b32 v96, v86, v22
	v_pk_mul_f32 v[16:17], v[8:9], v[24:25]
	v_pk_mul_f32 v[18:19], v[10:11], v[26:27]
	s_waitcnt lgkmcnt(2)
	v_add_f32_e32 v20, v20, v23
	s_waitcnt lgkmcnt(1)
	v_add_f32_e32 v21, v21, v91
	s_waitcnt lgkmcnt(0)
	v_add_f32_e32 v22, v22, v96
	ds_bpermute_b32 v23, v87, v20
	ds_bpermute_b32 v24, v87, v21
	ds_bpermute_b32 v25, v87, v22
	global_store_dwordx4 v[82:83], v[16:19], off offset:1024
	s_waitcnt lgkmcnt(2)
	v_add_f32_e32 v20, v20, v23
	s_waitcnt lgkmcnt(1)
	v_add_f32_e32 v21, v21, v24
	s_waitcnt lgkmcnt(0)
	v_add_f32_e32 v22, v22, v25
	ds_bpermute_b32 v23, v88, v20
	ds_bpermute_b32 v24, v88, v21
	ds_bpermute_b32 v25, v88, v22
	v_pk_mul_f32 v[18:19], v[6:7], v[30:31]
	v_pk_mul_f32 v[16:17], v[4:5], v[28:29]
	global_store_dwordx4 v[82:83], v[16:19], off offset:2048
	s_waitcnt lgkmcnt(2)
	v_add_f32_e32 v20, v20, v23
	s_waitcnt lgkmcnt(1)
	v_add_f32_e32 v18, v21, v24
	s_waitcnt lgkmcnt(0)
	v_add_f32_e32 v16, v22, v25
	ds_bpermute_b32 v21, v89, v20
	ds_bpermute_b32 v19, v89, v18
	ds_bpermute_b32 v17, v89, v16
	v_pk_mul_f32 v[24:25], v[2:3], v[92:93]
	v_pk_mul_f32 v[22:23], v[0:1], v[94:95]
	global_store_dwordx4 v[82:83], v[22:25], off offset:3072
	s_cbranch_scc0 .LBB0_1605
	s_andn2_b64 vcc, exec, s[12:13]
	s_cbranch_vccz .LBB0_1606
